# FFN-up epilogues only: RMS partial sums prefetched once per tile
# speedup vs baseline: 1.0484x; 1.0053x over previous
.LBB0_237:
	v_lshl_add_u32 v140, s41, 8, v145
	v_ashrrev_i32_e32 v141, 31, v140
	v_lshlrev_b64 v[164:165], 6, v[140:141]
	v_lshl_add_u64 v[164:165], s[66:67], 0, v[164:165]
	v_and_b32_e32 v166, 48, v197
	v_mov_b32_e32 v167, 0
	v_lshl_add_u64 v[164:165], v[164:165], 0, v[166:167]
	s_mov_b64 s[20:21], 0x2000
	v_lshl_add_u64 v[166:167], v[164:165], 0, s[20:21]
	global_load_dwordx4 v[204:207], v[164:165], off
	global_load_dwordx4 v[208:211], v[164:165], off offset:1024
	global_load_dwordx4 v[212:215], v[164:165], off offset:2048
	global_load_dwordx4 v[216:219], v[164:165], off offset:3072
	global_load_dwordx4 v[220:223], v[166:167], off
	global_load_dwordx4 v[224:227], v[166:167], off offset:1024
	global_load_dwordx4 v[228:231], v[166:167], off offset:2048
	global_load_dwordx4 v[232:235], v[166:167], off offset:3072
	v_lshl_or_b32 v142, s40, 7, v162
	v_ashrrev_i32_e32 v143, 31, v142
	s_waitcnt vmcnt(0)
	v_add_f32_e32 v204, v204, v205
	v_add_f32_e32 v206, v206, v207
	v_add_f32_e32 v204, v204, v206
	v_mov_b32_e32 v205, v204
	s_nop 1
	v_permlane16_swap_b32_e32 v204, v205
	v_add_f32_e32 v204, v204, v205
	v_mov_b32_e32 v205, v204
	s_nop 1
	v_permlane32_swap_b32_e32 v204, v205
	v_add_f32_e32 v141, v204, v205
	v_fmamk_f32 v141, v141, 0x3a800000, v161
	v_cmp_gt_f32_e32 vcc, s62, v141
	v_mul_f32_e32 v144, 0x4b800000, v141
	s_nop 0
	v_cndmask_b32_e32 v141, v141, v144, vcc
	v_rsq_f32_e32 v141, v141
	s_nop 0
	v_mul_f32_e32 v144, 0x45800000, v141
	v_cndmask_b32_e32 v144, v141, v144, vcc
	v_pk_mul_f32 v[126:127], v[126:127], v[144:145] op_sel_hi:[1,0]
	v_pk_mul_f32 v[122:123], v[122:123], v[144:145] op_sel_hi:[1,0]
	v_mul_f32_e32 v141, 0xbfb8aa3b, v126
	v_exp_f32_e32 v141, v141
	v_pk_mul_f32 v[124:125], v[124:125], v[144:145] op_sel_hi:[1,0]
	v_pk_mul_f32 v[118:119], v[118:119], v[144:145] op_sel_hi:[1,0]
	v_pk_mul_f32 v[114:115], v[114:115], v[144:145] op_sel_hi:[1,0]
	v_add_f32_e32 v141, 1.0, v141
	v_rcp_f32_e32 v164, v141
	v_mul_f32_e32 v141, 0xbfb8aa3b, v127
	v_exp_f32_e32 v141, v141
	v_pk_mul_f32 v[116:117], v[116:117], v[144:145] op_sel_hi:[1,0]
	v_add_f32_e32 v141, 1.0, v141
	v_rcp_f32_e32 v165, v141
	s_nop 0
	v_pk_mul_f32 v[126:127], v[126:127], v[164:165]
	s_nop 0
	v_pk_mul_f32 v[122:123], v[122:123], v[126:127]
	v_pk_mul_f32 v[126:127], v[128:129], v[144:145] op_sel_hi:[1,0]
	s_nop 0
	v_mul_f32_e32 v128, 0xbfb8aa3b, v126
	v_mul_f32_e32 v129, 0xbfb8aa3b, v127
	v_exp_f32_e32 v128, v128
	v_exp_f32_e32 v129, v129
	v_add_f32_e32 v128, 1.0, v128
	v_add_f32_e32 v129, 1.0, v129
	v_rcp_f32_e32 v128, v128
	v_rcp_f32_e32 v129, v129
	s_nop 0
	v_pk_mul_f32 v[126:127], v[126:127], v[128:129]
	s_nop 0
	v_pk_mul_f32 v[124:125], v[124:125], v[126:127]
	v_cvt_pk_bf16_f32 v126, v122, v123
	v_mov_b64_e32 v[122:123], s[8:9]
	v_cvt_pk_bf16_f32 v127, v124, v125
	v_mad_i64_i32 v[128:129], s[20:21], v140, s1, v[122:123]
	v_lshlrev_b64 v[124:125], 1, v[142:143]
	v_lshl_add_u64 v[128:129], v[128:129], 0, v[124:125]
	global_store_dwordx2 v[128:129], v[126:127], off
	v_mul_f32_e32 v126, 0xbfb8aa3b, v118
	v_mul_f32_e32 v127, 0xbfb8aa3b, v119
	v_exp_f32_e32 v126, v126
	v_exp_f32_e32 v127, v127
	v_add_f32_e32 v126, 1.0, v126
	v_add_f32_e32 v127, 1.0, v127
	v_rcp_f32_e32 v126, v126
	v_rcp_f32_e32 v127, v127
	s_nop 0
	v_pk_mul_f32 v[118:119], v[118:119], v[126:127]
	s_nop 0
	v_pk_mul_f32 v[114:115], v[114:115], v[118:119]
	v_pk_mul_f32 v[118:119], v[120:121], v[144:145] op_sel_hi:[1,0]
	v_or_b32_e32 v126, 16, v140
	v_mul_f32_e32 v120, 0xbfb8aa3b, v118
	v_mul_f32_e32 v121, 0xbfb8aa3b, v119
	v_exp_f32_e32 v120, v120
	v_exp_f32_e32 v121, v121
	v_cvt_pk_bf16_f32 v114, v114, v115
	v_ashrrev_i32_e32 v127, 31, v126
	v_add_f32_e32 v120, 1.0, v120
	v_add_f32_e32 v121, 1.0, v121
	v_rcp_f32_e32 v120, v120
	v_rcp_f32_e32 v121, v121
	s_nop 0
	v_pk_mul_f32 v[118:119], v[118:119], v[120:121]
	s_nop 0
	v_pk_mul_f32 v[116:117], v[116:117], v[118:119]
	s_nop 0
	v_cvt_pk_bf16_f32 v115, v116, v117
	global_store_dwordx2 v[128:129], v[114:115], off offset:128
	v_add_f32_e32 v208, v208, v209
	v_add_f32_e32 v210, v210, v211
	v_add_f32_e32 v208, v208, v210
	v_mov_b32_e32 v209, v208
	s_nop 1
	v_permlane16_swap_b32_e32 v208, v209
	v_add_f32_e32 v208, v208, v209
	v_mov_b32_e32 v209, v208
	s_nop 1
	v_permlane32_swap_b32_e32 v208, v209
	v_add_f32_e32 v114, v208, v209
	v_fmamk_f32 v114, v114, 0x3a800000, v161
	v_cmp_gt_f32_e32 vcc, s62, v114
	v_mul_f32_e32 v115, 0x4b800000, v114
	s_nop 0
	v_cndmask_b32_e32 v114, v114, v115, vcc
	v_rsq_f32_e32 v114, v114
	s_nop 0
	v_mul_f32_e32 v115, 0x45800000, v114
	v_cndmask_b32_e32 v114, v114, v115, vcc
	v_pk_mul_f32 v[110:111], v[110:111], v[114:115] op_sel_hi:[1,0]
	s_nop 0
	v_mul_f32_e32 v115, 0xbfb8aa3b, v110
	v_exp_f32_e32 v115, v115
	s_nop 0
	v_add_f32_e32 v115, 1.0, v115
	v_rcp_f32_e32 v116, v115
	v_mul_f32_e32 v115, 0xbfb8aa3b, v111
	v_exp_f32_e32 v115, v115
	s_nop 0
	v_add_f32_e32 v115, 1.0, v115
	v_rcp_f32_e32 v117, v115
	v_pk_mul_f32 v[106:107], v[106:107], v[114:115] op_sel_hi:[1,0]
	v_pk_mul_f32 v[108:109], v[108:109], v[114:115] op_sel_hi:[1,0]
	v_pk_mul_f32 v[102:103], v[102:103], v[114:115] op_sel_hi:[1,0]
	v_pk_mul_f32 v[110:111], v[110:111], v[116:117]
	v_pk_mul_f32 v[98:99], v[98:99], v[114:115] op_sel_hi:[1,0]
	v_pk_mul_f32 v[106:107], v[106:107], v[110:111]
	v_pk_mul_f32 v[110:111], v[112:113], v[114:115] op_sel_hi:[1,0]
	v_cvt_pk_bf16_f32 v106, v106, v107
	v_mul_f32_e32 v112, 0xbfb8aa3b, v110
	v_mul_f32_e32 v113, 0xbfb8aa3b, v111
	v_exp_f32_e32 v112, v112
	v_exp_f32_e32 v113, v113
	v_pk_mul_f32 v[100:101], v[100:101], v[114:115] op_sel_hi:[1,0]
	v_add_f32_e32 v112, 1.0, v112
	v_add_f32_e32 v113, 1.0, v113
	v_rcp_f32_e32 v112, v112
	v_rcp_f32_e32 v113, v113
	s_nop 0
	v_pk_mul_f32 v[110:111], v[110:111], v[112:113]
	s_nop 0
	v_pk_mul_f32 v[108:109], v[108:109], v[110:111]
	s_nop 0
	v_cvt_pk_bf16_f32 v107, v108, v109
	v_mad_i64_i32 v[108:109], s[20:21], v126, s1, v[122:123]
	v_lshl_add_u64 v[108:109], v[108:109], 0, v[124:125]
	global_store_dwordx2 v[108:109], v[106:107], off
	v_mul_f32_e32 v106, 0xbfb8aa3b, v102
	v_mul_f32_e32 v107, 0xbfb8aa3b, v103
	v_exp_f32_e32 v106, v106
	v_exp_f32_e32 v107, v107
	v_add_f32_e32 v106, 1.0, v106
	v_add_f32_e32 v107, 1.0, v107
	v_rcp_f32_e32 v106, v106
	v_rcp_f32_e32 v107, v107
	s_nop 0
	v_pk_mul_f32 v[102:103], v[102:103], v[106:107]
	s_nop 0
	v_pk_mul_f32 v[98:99], v[98:99], v[102:103]
	v_pk_mul_f32 v[102:103], v[104:105], v[114:115] op_sel_hi:[1,0]
	v_or_b32_e32 v106, 32, v140
	v_mul_f32_e32 v104, 0xbfb8aa3b, v102
	v_mul_f32_e32 v105, 0xbfb8aa3b, v103
	v_exp_f32_e32 v104, v104
	v_exp_f32_e32 v105, v105
	v_cvt_pk_bf16_f32 v98, v98, v99
	v_ashrrev_i32_e32 v107, 31, v106
	v_add_f32_e32 v104, 1.0, v104
	v_add_f32_e32 v105, 1.0, v105
	v_rcp_f32_e32 v104, v104
	v_rcp_f32_e32 v105, v105
	s_nop 0
	v_pk_mul_f32 v[102:103], v[102:103], v[104:105]
	s_nop 0
	v_pk_mul_f32 v[100:101], v[100:101], v[102:103]
	s_nop 0
	v_cvt_pk_bf16_f32 v99, v100, v101
	global_store_dwordx2 v[108:109], v[98:99], off offset:128
	v_add_f32_e32 v212, v212, v213
	v_add_f32_e32 v214, v214, v215
	v_add_f32_e32 v212, v212, v214
	v_mov_b32_e32 v213, v212
	s_nop 1
	v_permlane16_swap_b32_e32 v212, v213
	v_add_f32_e32 v212, v212, v213
	v_mov_b32_e32 v213, v212
	s_nop 1
	v_permlane32_swap_b32_e32 v212, v213
	v_add_f32_e32 v98, v212, v213
	v_fmamk_f32 v98, v98, 0x3a800000, v161
	v_cmp_gt_f32_e32 vcc, s62, v98
	v_mul_f32_e32 v99, 0x4b800000, v98
	s_nop 0
	v_cndmask_b32_e32 v98, v98, v99, vcc
	v_rsq_f32_e32 v98, v98
	s_nop 0
	v_mul_f32_e32 v99, 0x45800000, v98
	v_cndmask_b32_e32 v98, v98, v99, vcc
	v_pk_mul_f32 v[94:95], v[94:95], v[98:99] op_sel_hi:[1,0]
	s_nop 0
	v_mul_f32_e32 v99, 0xbfb8aa3b, v94
	v_exp_f32_e32 v99, v99
	s_nop 0
	v_add_f32_e32 v99, 1.0, v99
	v_rcp_f32_e32 v100, v99
	v_mul_f32_e32 v99, 0xbfb8aa3b, v95
	v_exp_f32_e32 v99, v99
	s_nop 0
	v_add_f32_e32 v99, 1.0, v99
	v_rcp_f32_e32 v101, v99
	v_pk_mul_f32 v[90:91], v[90:91], v[98:99] op_sel_hi:[1,0]
	v_pk_mul_f32 v[92:93], v[92:93], v[98:99] op_sel_hi:[1,0]
	v_pk_mul_f32 v[86:87], v[86:87], v[98:99] op_sel_hi:[1,0]
	v_pk_mul_f32 v[94:95], v[94:95], v[100:101]
	v_pk_mul_f32 v[82:83], v[82:83], v[98:99] op_sel_hi:[1,0]
	v_pk_mul_f32 v[90:91], v[90:91], v[94:95]
	v_pk_mul_f32 v[94:95], v[96:97], v[98:99] op_sel_hi:[1,0]
	v_cvt_pk_bf16_f32 v90, v90, v91
	v_mul_f32_e32 v96, 0xbfb8aa3b, v94
	v_mul_f32_e32 v97, 0xbfb8aa3b, v95
	v_exp_f32_e32 v96, v96
	v_exp_f32_e32 v97, v97
	v_pk_mul_f32 v[84:85], v[84:85], v[98:99] op_sel_hi:[1,0]
	v_add_f32_e32 v96, 1.0, v96
	v_add_f32_e32 v97, 1.0, v97
	v_rcp_f32_e32 v96, v96
	v_rcp_f32_e32 v97, v97
	s_nop 0
	v_pk_mul_f32 v[94:95], v[94:95], v[96:97]
	s_nop 0
	v_pk_mul_f32 v[92:93], v[92:93], v[94:95]
	s_nop 0
	v_cvt_pk_bf16_f32 v91, v92, v93
	v_mad_i64_i32 v[92:93], s[20:21], v106, s1, v[122:123]
	v_lshl_add_u64 v[92:93], v[92:93], 0, v[124:125]
	global_store_dwordx2 v[92:93], v[90:91], off
	v_mul_f32_e32 v90, 0xbfb8aa3b, v86
	v_mul_f32_e32 v91, 0xbfb8aa3b, v87
	v_exp_f32_e32 v90, v90
	v_exp_f32_e32 v91, v91
	v_add_f32_e32 v90, 1.0, v90
	v_add_f32_e32 v91, 1.0, v91
	v_rcp_f32_e32 v90, v90
	v_rcp_f32_e32 v91, v91
	s_nop 0
	v_pk_mul_f32 v[86:87], v[86:87], v[90:91]
	s_nop 0
	v_pk_mul_f32 v[82:83], v[82:83], v[86:87]
	v_pk_mul_f32 v[86:87], v[88:89], v[98:99] op_sel_hi:[1,0]
	v_or_b32_e32 v90, 48, v140
	v_mul_f32_e32 v88, 0xbfb8aa3b, v86
	v_mul_f32_e32 v89, 0xbfb8aa3b, v87
	v_exp_f32_e32 v88, v88
	v_exp_f32_e32 v89, v89
	v_cvt_pk_bf16_f32 v82, v82, v83
	v_ashrrev_i32_e32 v91, 31, v90
	v_add_f32_e32 v88, 1.0, v88
	v_add_f32_e32 v89, 1.0, v89
	v_rcp_f32_e32 v88, v88
	v_rcp_f32_e32 v89, v89
	s_nop 0
	v_pk_mul_f32 v[86:87], v[86:87], v[88:89]
	s_nop 0
	v_pk_mul_f32 v[84:85], v[84:85], v[86:87]
	s_nop 0
	v_cvt_pk_bf16_f32 v83, v84, v85
	global_store_dwordx2 v[92:93], v[82:83], off offset:128
	v_add_f32_e32 v216, v216, v217
	v_add_f32_e32 v218, v218, v219
	v_add_f32_e32 v216, v216, v218
	v_mov_b32_e32 v217, v216
	s_nop 1
	v_permlane16_swap_b32_e32 v216, v217
	v_add_f32_e32 v216, v216, v217
	v_mov_b32_e32 v217, v216
	s_nop 1
	v_permlane32_swap_b32_e32 v216, v217
	v_add_f32_e32 v82, v216, v217
	v_fmamk_f32 v82, v82, 0x3a800000, v161
	v_cmp_gt_f32_e32 vcc, s62, v82
	v_mul_f32_e32 v83, 0x4b800000, v82
	s_nop 0
	v_cndmask_b32_e32 v82, v82, v83, vcc
	v_rsq_f32_e32 v82, v82
	s_nop 0
	v_mul_f32_e32 v83, 0x45800000, v82
	v_cndmask_b32_e32 v82, v82, v83, vcc
	v_pk_mul_f32 v[78:79], v[78:79], v[82:83] op_sel_hi:[1,0]
	s_nop 0
	v_mul_f32_e32 v83, 0xbfb8aa3b, v78
	v_exp_f32_e32 v83, v83
	s_nop 0
	v_add_f32_e32 v83, 1.0, v83
	v_rcp_f32_e32 v84, v83
	v_mul_f32_e32 v83, 0xbfb8aa3b, v79
	v_exp_f32_e32 v83, v83
	s_nop 0
	v_add_f32_e32 v83, 1.0, v83
	v_rcp_f32_e32 v85, v83
	v_pk_mul_f32 v[74:75], v[74:75], v[82:83] op_sel_hi:[1,0]
	v_pk_mul_f32 v[76:77], v[76:77], v[82:83] op_sel_hi:[1,0]
	v_pk_mul_f32 v[70:71], v[70:71], v[82:83] op_sel_hi:[1,0]
	v_pk_mul_f32 v[78:79], v[78:79], v[84:85]
	v_pk_mul_f32 v[66:67], v[66:67], v[82:83] op_sel_hi:[1,0]
	v_pk_mul_f32 v[74:75], v[74:75], v[78:79]
	v_pk_mul_f32 v[78:79], v[80:81], v[82:83] op_sel_hi:[1,0]
	v_cvt_pk_bf16_f32 v74, v74, v75
	v_mul_f32_e32 v80, 0xbfb8aa3b, v78
	v_mul_f32_e32 v81, 0xbfb8aa3b, v79
	v_exp_f32_e32 v80, v80
	v_exp_f32_e32 v81, v81
	v_pk_mul_f32 v[68:69], v[68:69], v[82:83] op_sel_hi:[1,0]
	v_add_f32_e32 v80, 1.0, v80
	v_add_f32_e32 v81, 1.0, v81
	v_rcp_f32_e32 v80, v80
	v_rcp_f32_e32 v81, v81
	s_nop 0
	v_pk_mul_f32 v[78:79], v[78:79], v[80:81]
	s_nop 0
	v_pk_mul_f32 v[76:77], v[76:77], v[78:79]
	s_nop 0
	v_cvt_pk_bf16_f32 v75, v76, v77
	v_mad_i64_i32 v[76:77], s[20:21], v90, s1, v[122:123]
	v_lshl_add_u64 v[76:77], v[76:77], 0, v[124:125]
	global_store_dwordx2 v[76:77], v[74:75], off
	v_mul_f32_e32 v74, 0xbfb8aa3b, v70
	v_mul_f32_e32 v75, 0xbfb8aa3b, v71
	v_exp_f32_e32 v74, v74
	v_exp_f32_e32 v75, v75
	v_add_f32_e32 v74, 1.0, v74
	v_add_f32_e32 v75, 1.0, v75
	v_rcp_f32_e32 v74, v74
	v_rcp_f32_e32 v75, v75
	s_nop 0
	v_pk_mul_f32 v[70:71], v[70:71], v[74:75]
	s_nop 0
	v_pk_mul_f32 v[66:67], v[66:67], v[70:71]
	v_pk_mul_f32 v[70:71], v[72:73], v[82:83] op_sel_hi:[1,0]
	v_add_u32_e32 v74, 0x80, v140
	v_mul_f32_e32 v72, 0xbfb8aa3b, v70
	v_mul_f32_e32 v73, 0xbfb8aa3b, v71
	v_exp_f32_e32 v72, v72
	v_exp_f32_e32 v73, v73
	v_cvt_pk_bf16_f32 v66, v66, v67
	v_ashrrev_i32_e32 v75, 31, v74
	v_add_f32_e32 v72, 1.0, v72
	v_add_f32_e32 v73, 1.0, v73
	v_rcp_f32_e32 v72, v72
	v_rcp_f32_e32 v73, v73
	s_nop 0
	v_pk_mul_f32 v[70:71], v[70:71], v[72:73]
	s_nop 0
	v_pk_mul_f32 v[68:69], v[68:69], v[70:71]
	s_nop 0
	v_cvt_pk_bf16_f32 v67, v68, v69
	global_store_dwordx2 v[76:77], v[66:67], off offset:128
	v_add_f32_e32 v220, v220, v221
	v_add_f32_e32 v222, v222, v223
	v_add_f32_e32 v220, v220, v222
	v_mov_b32_e32 v221, v220
	s_nop 1
	v_permlane16_swap_b32_e32 v220, v221
	v_add_f32_e32 v220, v220, v221
	v_mov_b32_e32 v221, v220
	s_nop 1
	v_permlane32_swap_b32_e32 v220, v221
	v_add_f32_e32 v66, v220, v221
	v_fmamk_f32 v66, v66, 0x3a800000, v161
	v_cmp_gt_f32_e32 vcc, s62, v66
	v_mul_f32_e32 v67, 0x4b800000, v66
	s_nop 0
	v_cndmask_b32_e32 v66, v66, v67, vcc
	v_rsq_f32_e32 v66, v66
	s_nop 0
	v_mul_f32_e32 v67, 0x45800000, v66
	v_cndmask_b32_e32 v66, v66, v67, vcc
	v_pk_mul_f32 v[62:63], v[62:63], v[66:67] op_sel_hi:[1,0]
	s_nop 0
	v_mul_f32_e32 v67, 0xbfb8aa3b, v62
	v_exp_f32_e32 v67, v67
	s_nop 0
	v_add_f32_e32 v67, 1.0, v67
	v_rcp_f32_e32 v68, v67
	v_mul_f32_e32 v67, 0xbfb8aa3b, v63
	v_exp_f32_e32 v67, v67
	s_nop 0
	v_add_f32_e32 v67, 1.0, v67
	v_rcp_f32_e32 v69, v67
	v_pk_mul_f32 v[58:59], v[58:59], v[66:67] op_sel_hi:[1,0]
	v_pk_mul_f32 v[60:61], v[60:61], v[66:67] op_sel_hi:[1,0]
	v_pk_mul_f32 v[54:55], v[54:55], v[66:67] op_sel_hi:[1,0]
	v_pk_mul_f32 v[62:63], v[62:63], v[68:69]
	v_pk_mul_f32 v[50:51], v[50:51], v[66:67] op_sel_hi:[1,0]
	v_pk_mul_f32 v[58:59], v[58:59], v[62:63]
	v_pk_mul_f32 v[62:63], v[64:65], v[66:67] op_sel_hi:[1,0]
	v_cvt_pk_bf16_f32 v58, v58, v59
	v_mul_f32_e32 v64, 0xbfb8aa3b, v62
	v_mul_f32_e32 v65, 0xbfb8aa3b, v63
	v_exp_f32_e32 v64, v64
	v_exp_f32_e32 v65, v65
	v_pk_mul_f32 v[52:53], v[52:53], v[66:67] op_sel_hi:[1,0]
	v_add_f32_e32 v64, 1.0, v64
	v_add_f32_e32 v65, 1.0, v65
	v_rcp_f32_e32 v64, v64
	v_rcp_f32_e32 v65, v65
	s_nop 0
	v_pk_mul_f32 v[62:63], v[62:63], v[64:65]
	s_nop 0
	v_pk_mul_f32 v[60:61], v[60:61], v[62:63]
	s_nop 0
	v_cvt_pk_bf16_f32 v59, v60, v61
	v_mad_i64_i32 v[60:61], s[20:21], v74, s1, v[122:123]
	v_lshl_add_u64 v[60:61], v[60:61], 0, v[124:125]
	global_store_dwordx2 v[60:61], v[58:59], off
	v_mul_f32_e32 v58, 0xbfb8aa3b, v54
	v_mul_f32_e32 v59, 0xbfb8aa3b, v55
	v_exp_f32_e32 v58, v58
	v_exp_f32_e32 v59, v59
	v_add_f32_e32 v58, 1.0, v58
	v_add_f32_e32 v59, 1.0, v59
	v_rcp_f32_e32 v58, v58
	v_rcp_f32_e32 v59, v59
	s_nop 0
	v_pk_mul_f32 v[54:55], v[54:55], v[58:59]
	s_nop 0
	v_pk_mul_f32 v[50:51], v[50:51], v[54:55]
	v_pk_mul_f32 v[54:55], v[56:57], v[66:67] op_sel_hi:[1,0]
	v_add_u32_e32 v58, 0x90, v140
	v_mul_f32_e32 v56, 0xbfb8aa3b, v54
	v_mul_f32_e32 v57, 0xbfb8aa3b, v55
	v_exp_f32_e32 v56, v56
	v_exp_f32_e32 v57, v57
	v_cvt_pk_bf16_f32 v50, v50, v51
	v_ashrrev_i32_e32 v59, 31, v58
	v_add_f32_e32 v56, 1.0, v56
	v_add_f32_e32 v57, 1.0, v57
	v_rcp_f32_e32 v56, v56
	v_rcp_f32_e32 v57, v57
	s_nop 0
	v_pk_mul_f32 v[54:55], v[54:55], v[56:57]
	s_nop 0
	v_pk_mul_f32 v[52:53], v[52:53], v[54:55]
	s_nop 0
	v_cvt_pk_bf16_f32 v51, v52, v53
	global_store_dwordx2 v[60:61], v[50:51], off offset:128
	v_add_f32_e32 v224, v224, v225
	v_add_f32_e32 v226, v226, v227
	v_add_f32_e32 v224, v224, v226
	v_mov_b32_e32 v225, v224
	s_nop 1
	v_permlane16_swap_b32_e32 v224, v225
	v_add_f32_e32 v224, v224, v225
	v_mov_b32_e32 v225, v224
	s_nop 1
	v_permlane32_swap_b32_e32 v224, v225
	v_add_f32_e32 v50, v224, v225
	v_fmamk_f32 v50, v50, 0x3a800000, v161
	v_cmp_gt_f32_e32 vcc, s62, v50
	v_mul_f32_e32 v51, 0x4b800000, v50
	s_nop 0
	v_cndmask_b32_e32 v50, v50, v51, vcc
	v_rsq_f32_e32 v50, v50
	s_nop 0
	v_mul_f32_e32 v51, 0x45800000, v50
	v_cndmask_b32_e32 v50, v50, v51, vcc
	v_pk_mul_f32 v[46:47], v[46:47], v[50:51] op_sel_hi:[1,0]
	s_nop 0
	v_mul_f32_e32 v51, 0xbfb8aa3b, v46
	v_exp_f32_e32 v51, v51
	s_nop 0
	v_add_f32_e32 v51, 1.0, v51
	v_rcp_f32_e32 v52, v51
	v_mul_f32_e32 v51, 0xbfb8aa3b, v47
	v_exp_f32_e32 v51, v51
	s_nop 0
	v_add_f32_e32 v51, 1.0, v51
	v_rcp_f32_e32 v53, v51
	v_pk_mul_f32 v[42:43], v[42:43], v[50:51] op_sel_hi:[1,0]
	v_pk_mul_f32 v[44:45], v[44:45], v[50:51] op_sel_hi:[1,0]
	v_pk_mul_f32 v[38:39], v[38:39], v[50:51] op_sel_hi:[1,0]
	v_pk_mul_f32 v[46:47], v[46:47], v[52:53]
	v_pk_mul_f32 v[34:35], v[34:35], v[50:51] op_sel_hi:[1,0]
	v_pk_mul_f32 v[42:43], v[42:43], v[46:47]
	v_pk_mul_f32 v[46:47], v[48:49], v[50:51] op_sel_hi:[1,0]
	v_cvt_pk_bf16_f32 v42, v42, v43
	v_mul_f32_e32 v48, 0xbfb8aa3b, v46
	v_mul_f32_e32 v49, 0xbfb8aa3b, v47
	v_exp_f32_e32 v48, v48
	v_exp_f32_e32 v49, v49
	v_pk_mul_f32 v[36:37], v[36:37], v[50:51] op_sel_hi:[1,0]
	v_add_f32_e32 v48, 1.0, v48
	v_add_f32_e32 v49, 1.0, v49
	v_rcp_f32_e32 v48, v48
	v_rcp_f32_e32 v49, v49
	s_nop 0
	v_pk_mul_f32 v[46:47], v[46:47], v[48:49]
	s_nop 0
	v_pk_mul_f32 v[44:45], v[44:45], v[46:47]
	s_nop 0
	v_cvt_pk_bf16_f32 v43, v44, v45
	v_mad_i64_i32 v[44:45], s[20:21], v58, s1, v[122:123]
	v_lshl_add_u64 v[44:45], v[44:45], 0, v[124:125]
	global_store_dwordx2 v[44:45], v[42:43], off
	v_mul_f32_e32 v42, 0xbfb8aa3b, v38
	v_mul_f32_e32 v43, 0xbfb8aa3b, v39
	v_exp_f32_e32 v42, v42
	v_exp_f32_e32 v43, v43
	v_add_f32_e32 v42, 1.0, v42
	v_add_f32_e32 v43, 1.0, v43
	v_rcp_f32_e32 v42, v42
	v_rcp_f32_e32 v43, v43
	s_nop 0
	v_pk_mul_f32 v[38:39], v[38:39], v[42:43]
	s_nop 0
	v_pk_mul_f32 v[34:35], v[34:35], v[38:39]
	v_pk_mul_f32 v[38:39], v[40:41], v[50:51] op_sel_hi:[1,0]
	v_add_u32_e32 v42, 0xa0, v140
	v_mul_f32_e32 v40, 0xbfb8aa3b, v38
	v_mul_f32_e32 v41, 0xbfb8aa3b, v39
	v_exp_f32_e32 v40, v40
	v_exp_f32_e32 v41, v41
	v_cvt_pk_bf16_f32 v34, v34, v35
	v_ashrrev_i32_e32 v43, 31, v42
	v_add_f32_e32 v40, 1.0, v40
	v_add_f32_e32 v41, 1.0, v41
	v_rcp_f32_e32 v40, v40
	v_rcp_f32_e32 v41, v41
	s_nop 0
	v_pk_mul_f32 v[38:39], v[38:39], v[40:41]
	s_nop 0
	v_pk_mul_f32 v[36:37], v[36:37], v[38:39]
	s_nop 0
	v_cvt_pk_bf16_f32 v35, v36, v37
	global_store_dwordx2 v[44:45], v[34:35], off offset:128
	v_add_f32_e32 v228, v228, v229
	v_add_f32_e32 v230, v230, v231
	v_add_f32_e32 v228, v228, v230
	v_mov_b32_e32 v229, v228
	s_nop 1
	v_permlane16_swap_b32_e32 v228, v229
	v_add_f32_e32 v228, v228, v229
	v_mov_b32_e32 v229, v228
	s_nop 1
	v_permlane32_swap_b32_e32 v228, v229
	v_add_f32_e32 v34, v228, v229
	v_fmamk_f32 v34, v34, 0x3a800000, v161
	v_cmp_gt_f32_e32 vcc, s62, v34
	v_mul_f32_e32 v35, 0x4b800000, v34
	s_nop 0
	v_cndmask_b32_e32 v34, v34, v35, vcc
	v_rsq_f32_e32 v34, v34
	s_nop 0
	v_mul_f32_e32 v35, 0x45800000, v34
	v_cndmask_b32_e32 v34, v34, v35, vcc
	v_pk_mul_f32 v[30:31], v[30:31], v[34:35] op_sel_hi:[1,0]
	s_nop 0
	v_mul_f32_e32 v35, 0xbfb8aa3b, v30
	v_exp_f32_e32 v35, v35
	s_nop 0
	v_add_f32_e32 v35, 1.0, v35
	v_rcp_f32_e32 v36, v35
	v_mul_f32_e32 v35, 0xbfb8aa3b, v31
	v_exp_f32_e32 v35, v35
	s_nop 0
	v_add_f32_e32 v35, 1.0, v35
	v_rcp_f32_e32 v37, v35
	v_pk_mul_f32 v[26:27], v[26:27], v[34:35] op_sel_hi:[1,0]
	v_pk_mul_f32 v[28:29], v[28:29], v[34:35] op_sel_hi:[1,0]
	v_pk_mul_f32 v[22:23], v[22:23], v[34:35] op_sel_hi:[1,0]
	v_pk_mul_f32 v[30:31], v[30:31], v[36:37]
	v_pk_mul_f32 v[18:19], v[18:19], v[34:35] op_sel_hi:[1,0]
	v_pk_mul_f32 v[26:27], v[26:27], v[30:31]
	v_pk_mul_f32 v[30:31], v[32:33], v[34:35] op_sel_hi:[1,0]
	v_cvt_pk_bf16_f32 v26, v26, v27
	v_mul_f32_e32 v32, 0xbfb8aa3b, v30
	v_mul_f32_e32 v33, 0xbfb8aa3b, v31
	v_exp_f32_e32 v32, v32
	v_exp_f32_e32 v33, v33
	v_pk_mul_f32 v[20:21], v[20:21], v[34:35] op_sel_hi:[1,0]
	v_add_f32_e32 v32, 1.0, v32
	v_add_f32_e32 v33, 1.0, v33
	v_rcp_f32_e32 v32, v32
	v_rcp_f32_e32 v33, v33
	s_nop 0
	v_pk_mul_f32 v[30:31], v[30:31], v[32:33]
	s_nop 0
	v_pk_mul_f32 v[28:29], v[28:29], v[30:31]
	s_nop 0
	v_cvt_pk_bf16_f32 v27, v28, v29
	v_mad_i64_i32 v[28:29], s[20:21], v42, s1, v[122:123]
	v_lshl_add_u64 v[28:29], v[28:29], 0, v[124:125]
	global_store_dwordx2 v[28:29], v[26:27], off
	v_mul_f32_e32 v26, 0xbfb8aa3b, v22
	v_mul_f32_e32 v27, 0xbfb8aa3b, v23
	v_exp_f32_e32 v26, v26
	v_exp_f32_e32 v27, v27
	v_add_f32_e32 v26, 1.0, v26
	v_add_f32_e32 v27, 1.0, v27
	v_rcp_f32_e32 v26, v26
	v_rcp_f32_e32 v27, v27
	s_nop 0
	v_pk_mul_f32 v[22:23], v[22:23], v[26:27]
	s_nop 0
	v_pk_mul_f32 v[18:19], v[18:19], v[22:23]
	v_pk_mul_f32 v[22:23], v[24:25], v[34:35] op_sel_hi:[1,0]
	v_add_u32_e32 v26, 0xb0, v140
	v_mul_f32_e32 v24, 0xbfb8aa3b, v22
	v_mul_f32_e32 v25, 0xbfb8aa3b, v23
	v_exp_f32_e32 v24, v24
	v_exp_f32_e32 v25, v25
	v_cvt_pk_bf16_f32 v18, v18, v19
	v_ashrrev_i32_e32 v27, 31, v26
	v_add_f32_e32 v24, 1.0, v24
	v_add_f32_e32 v25, 1.0, v25
	v_rcp_f32_e32 v24, v24
	v_rcp_f32_e32 v25, v25
	s_nop 0
	v_pk_mul_f32 v[22:23], v[22:23], v[24:25]
	s_nop 0
	v_pk_mul_f32 v[20:21], v[20:21], v[22:23]
	s_nop 0
	v_cvt_pk_bf16_f32 v19, v20, v21
	global_store_dwordx2 v[28:29], v[18:19], off offset:128
	v_add_f32_e32 v232, v232, v233
	v_add_f32_e32 v234, v234, v235
	v_add_f32_e32 v232, v232, v234
	v_mov_b32_e32 v233, v232
	s_nop 1
	v_permlane16_swap_b32_e32 v232, v233
	v_add_f32_e32 v232, v232, v233
	v_mov_b32_e32 v233, v232
	s_nop 1
	v_permlane32_swap_b32_e32 v232, v233
	v_add_f32_e32 v18, v232, v233
	v_fmamk_f32 v18, v18, 0x3a800000, v161
	v_cmp_gt_f32_e32 vcc, s62, v18
	v_mul_f32_e32 v19, 0x4b800000, v18
	s_nop 0
	v_cndmask_b32_e32 v18, v18, v19, vcc
	v_rsq_f32_e32 v18, v18
	s_nop 0
	v_mul_f32_e32 v19, 0x45800000, v18
	v_cndmask_b32_e32 v18, v18, v19, vcc
	v_pk_mul_f32 v[14:15], v[14:15], v[18:19] op_sel_hi:[1,0]
	s_andn2_b64 vcc, exec, s[4:5]
	v_mul_f32_e32 v19, 0xbfb8aa3b, v14
	v_exp_f32_e32 v19, v19
	s_nop 0
	v_add_f32_e32 v19, 1.0, v19
	v_rcp_f32_e32 v20, v19
	v_mul_f32_e32 v19, 0xbfb8aa3b, v15
	v_exp_f32_e32 v19, v19
	s_nop 0
	v_add_f32_e32 v19, 1.0, v19
	v_rcp_f32_e32 v21, v19
	v_pk_mul_f32 v[10:11], v[10:11], v[18:19] op_sel_hi:[1,0]
	v_pk_mul_f32 v[12:13], v[12:13], v[18:19] op_sel_hi:[1,0]
	v_pk_mul_f32 v[6:7], v[6:7], v[18:19] op_sel_hi:[1,0]
	v_pk_mul_f32 v[14:15], v[14:15], v[20:21]
	v_pk_mul_f32 v[2:3], v[2:3], v[18:19] op_sel_hi:[1,0]
	v_pk_mul_f32 v[10:11], v[10:11], v[14:15]
	v_pk_mul_f32 v[14:15], v[16:17], v[18:19] op_sel_hi:[1,0]
	v_cvt_pk_bf16_f32 v10, v10, v11
	v_mul_f32_e32 v16, 0xbfb8aa3b, v14
	v_mul_f32_e32 v17, 0xbfb8aa3b, v15
	v_exp_f32_e32 v16, v16
	v_exp_f32_e32 v17, v17
	v_pk_mul_f32 v[4:5], v[4:5], v[18:19] op_sel_hi:[1,0]
	v_add_f32_e32 v16, 1.0, v16
	v_add_f32_e32 v17, 1.0, v17
	v_rcp_f32_e32 v16, v16
	v_rcp_f32_e32 v17, v17
	s_nop 0
	v_pk_mul_f32 v[14:15], v[14:15], v[16:17]
	s_nop 0
	v_pk_mul_f32 v[12:13], v[12:13], v[14:15]
	s_nop 0
	v_cvt_pk_bf16_f32 v11, v12, v13
	v_mad_i64_i32 v[12:13], s[20:21], v26, s1, v[122:123]
	v_lshl_add_u64 v[12:13], v[12:13], 0, v[124:125]
	global_store_dwordx2 v[12:13], v[10:11], off
	v_mul_f32_e32 v10, 0xbfb8aa3b, v6
	v_mul_f32_e32 v11, 0xbfb8aa3b, v7
	v_exp_f32_e32 v10, v10
	v_exp_f32_e32 v11, v11
	s_mov_b64 s[20:21], -1
	v_add_f32_e32 v10, 1.0, v10
	v_add_f32_e32 v11, 1.0, v11
	v_rcp_f32_e32 v10, v10
	v_rcp_f32_e32 v11, v11
	s_nop 0
	v_pk_mul_f32 v[6:7], v[6:7], v[10:11]
	s_nop 0
	v_pk_mul_f32 v[2:3], v[2:3], v[6:7]
	v_pk_mul_f32 v[6:7], v[8:9], v[18:19] op_sel_hi:[1,0]
	v_cvt_pk_bf16_f32 v2, v2, v3
	v_mul_f32_e32 v8, 0xbfb8aa3b, v6
	v_mul_f32_e32 v9, 0xbfb8aa3b, v7
	v_exp_f32_e32 v8, v8
	v_exp_f32_e32 v9, v9
	v_add_f32_e32 v8, 1.0, v8
	v_add_f32_e32 v9, 1.0, v9
	v_rcp_f32_e32 v8, v8
	v_rcp_f32_e32 v9, v9
	s_nop 0
	v_pk_mul_f32 v[6:7], v[6:7], v[8:9]
	s_nop 0
	v_pk_mul_f32 v[4:5], v[4:5], v[6:7]
	s_nop 0
	v_cvt_pk_bf16_f32 v3, v4, v5
	global_store_dwordx2 v[12:13], v[2:3], off offset:128
	s_cbranch_vccnz .LBB0_230
	s_andn2_b64 vcc, exec, s[6:7]
	s_cbranch_vccnz .LBB0_229
	s_barrier
	s_branch .LBB0_229

.LBB0_1605:
	v_lshl_add_u32 v140, s41, 8, v145
	v_ashrrev_i32_e32 v141, 31, v140
	v_lshlrev_b64 v[164:165], 6, v[140:141]
	v_lshl_add_u64 v[164:165], s[66:67], 0, v[164:165]
	v_and_b32_e32 v166, 48, v197
	v_mov_b32_e32 v167, 0
	v_lshl_add_u64 v[164:165], v[164:165], 0, v[166:167]
	s_mov_b64 s[20:21], 0x2000
	v_lshl_add_u64 v[166:167], v[164:165], 0, s[20:21]
	global_load_dwordx4 v[204:207], v[164:165], off
	global_load_dwordx4 v[208:211], v[164:165], off offset:1024
	global_load_dwordx4 v[212:215], v[164:165], off offset:2048
	global_load_dwordx4 v[216:219], v[164:165], off offset:3072
	global_load_dwordx4 v[220:223], v[166:167], off
	global_load_dwordx4 v[224:227], v[166:167], off offset:1024
	global_load_dwordx4 v[228:231], v[166:167], off offset:2048
	global_load_dwordx4 v[232:235], v[166:167], off offset:3072
	v_lshl_or_b32 v142, s40, 7, v162
	v_ashrrev_i32_e32 v143, 31, v142
	s_waitcnt vmcnt(0)
	v_add_f32_e32 v204, v204, v205
	v_add_f32_e32 v206, v206, v207
	v_add_f32_e32 v204, v204, v206
	v_mov_b32_e32 v205, v204
	s_nop 1
	v_permlane16_swap_b32_e32 v204, v205
	v_add_f32_e32 v204, v204, v205
	v_mov_b32_e32 v205, v204
	s_nop 1
	v_permlane32_swap_b32_e32 v204, v205
	v_add_f32_e32 v141, v204, v205
	v_fmamk_f32 v141, v141, 0x3a800000, v161
	v_cmp_gt_f32_e32 vcc, s62, v141
	v_mul_f32_e32 v144, 0x4b800000, v141
	s_nop 0
	v_cndmask_b32_e32 v141, v141, v144, vcc
	v_rsq_f32_e32 v141, v141
	s_nop 0
	v_mul_f32_e32 v144, 0x45800000, v141
	v_cndmask_b32_e32 v144, v141, v144, vcc
	v_pk_mul_f32 v[126:127], v[126:127], v[144:145] op_sel_hi:[1,0]
	v_pk_mul_f32 v[122:123], v[122:123], v[144:145] op_sel_hi:[1,0]
	v_mul_f32_e32 v141, 0xbfb8aa3b, v126
	v_exp_f32_e32 v141, v141
	v_pk_mul_f32 v[124:125], v[124:125], v[144:145] op_sel_hi:[1,0]
	v_pk_mul_f32 v[118:119], v[118:119], v[144:145] op_sel_hi:[1,0]
	v_pk_mul_f32 v[114:115], v[114:115], v[144:145] op_sel_hi:[1,0]
	v_add_f32_e32 v141, 1.0, v141
	v_rcp_f32_e32 v164, v141
	v_mul_f32_e32 v141, 0xbfb8aa3b, v127
	v_exp_f32_e32 v141, v141
	v_pk_mul_f32 v[116:117], v[116:117], v[144:145] op_sel_hi:[1,0]
	v_add_f32_e32 v141, 1.0, v141
	v_rcp_f32_e32 v165, v141
	s_nop 0
	v_pk_mul_f32 v[126:127], v[126:127], v[164:165]
	s_nop 0
	v_pk_mul_f32 v[122:123], v[122:123], v[126:127]
	v_pk_mul_f32 v[126:127], v[128:129], v[144:145] op_sel_hi:[1,0]
	s_nop 0
	v_mul_f32_e32 v128, 0xbfb8aa3b, v126
	v_mul_f32_e32 v129, 0xbfb8aa3b, v127
	v_exp_f32_e32 v128, v128
	v_exp_f32_e32 v129, v129
	v_add_f32_e32 v128, 1.0, v128
	v_add_f32_e32 v129, 1.0, v129
	v_rcp_f32_e32 v128, v128
	v_rcp_f32_e32 v129, v129
	s_nop 0
	v_pk_mul_f32 v[126:127], v[126:127], v[128:129]
	s_nop 0
	v_pk_mul_f32 v[124:125], v[124:125], v[126:127]
	v_cvt_pk_bf16_f32 v126, v122, v123
	v_mov_b64_e32 v[122:123], s[8:9]
	v_cvt_pk_bf16_f32 v127, v124, v125
	v_mad_i64_i32 v[128:129], s[20:21], v140, s1, v[122:123]
	v_lshlrev_b64 v[124:125], 1, v[142:143]
	v_lshl_add_u64 v[128:129], v[128:129], 0, v[124:125]
	global_store_dwordx2 v[128:129], v[126:127], off
	v_mul_f32_e32 v126, 0xbfb8aa3b, v118
	v_mul_f32_e32 v127, 0xbfb8aa3b, v119
	v_exp_f32_e32 v126, v126
	v_exp_f32_e32 v127, v127
	v_add_f32_e32 v126, 1.0, v126
	v_add_f32_e32 v127, 1.0, v127
	v_rcp_f32_e32 v126, v126
	v_rcp_f32_e32 v127, v127
	s_nop 0
	v_pk_mul_f32 v[118:119], v[118:119], v[126:127]
	s_nop 0
	v_pk_mul_f32 v[114:115], v[114:115], v[118:119]
	v_pk_mul_f32 v[118:119], v[120:121], v[144:145] op_sel_hi:[1,0]
	v_or_b32_e32 v126, 16, v140
	v_mul_f32_e32 v120, 0xbfb8aa3b, v118
	v_mul_f32_e32 v121, 0xbfb8aa3b, v119
	v_exp_f32_e32 v120, v120
	v_exp_f32_e32 v121, v121
	v_cvt_pk_bf16_f32 v114, v114, v115
	v_ashrrev_i32_e32 v127, 31, v126
	v_add_f32_e32 v120, 1.0, v120
	v_add_f32_e32 v121, 1.0, v121
	v_rcp_f32_e32 v120, v120
	v_rcp_f32_e32 v121, v121
	s_nop 0
	v_pk_mul_f32 v[118:119], v[118:119], v[120:121]
	s_nop 0
	v_pk_mul_f32 v[116:117], v[116:117], v[118:119]
	s_nop 0
	v_cvt_pk_bf16_f32 v115, v116, v117
	global_store_dwordx2 v[128:129], v[114:115], off offset:128
	v_add_f32_e32 v208, v208, v209
	v_add_f32_e32 v210, v210, v211
	v_add_f32_e32 v208, v208, v210
	v_mov_b32_e32 v209, v208
	s_nop 1
	v_permlane16_swap_b32_e32 v208, v209
	v_add_f32_e32 v208, v208, v209
	v_mov_b32_e32 v209, v208
	s_nop 1
	v_permlane32_swap_b32_e32 v208, v209
	v_add_f32_e32 v114, v208, v209
	v_fmamk_f32 v114, v114, 0x3a800000, v161
	v_cmp_gt_f32_e32 vcc, s62, v114
	v_mul_f32_e32 v115, 0x4b800000, v114
	s_nop 0
	v_cndmask_b32_e32 v114, v114, v115, vcc
	v_rsq_f32_e32 v114, v114
	s_nop 0
	v_mul_f32_e32 v115, 0x45800000, v114
	v_cndmask_b32_e32 v114, v114, v115, vcc
	v_pk_mul_f32 v[110:111], v[110:111], v[114:115] op_sel_hi:[1,0]
	s_nop 0
	v_mul_f32_e32 v115, 0xbfb8aa3b, v110
	v_exp_f32_e32 v115, v115
	s_nop 0
	v_add_f32_e32 v115, 1.0, v115
	v_rcp_f32_e32 v116, v115
	v_mul_f32_e32 v115, 0xbfb8aa3b, v111
	v_exp_f32_e32 v115, v115
	s_nop 0
	v_add_f32_e32 v115, 1.0, v115
	v_rcp_f32_e32 v117, v115
	v_pk_mul_f32 v[106:107], v[106:107], v[114:115] op_sel_hi:[1,0]
	v_pk_mul_f32 v[108:109], v[108:109], v[114:115] op_sel_hi:[1,0]
	v_pk_mul_f32 v[102:103], v[102:103], v[114:115] op_sel_hi:[1,0]
	v_pk_mul_f32 v[110:111], v[110:111], v[116:117]
	v_pk_mul_f32 v[98:99], v[98:99], v[114:115] op_sel_hi:[1,0]
	v_pk_mul_f32 v[106:107], v[106:107], v[110:111]
	v_pk_mul_f32 v[110:111], v[112:113], v[114:115] op_sel_hi:[1,0]
	v_cvt_pk_bf16_f32 v106, v106, v107
	v_mul_f32_e32 v112, 0xbfb8aa3b, v110
	v_mul_f32_e32 v113, 0xbfb8aa3b, v111
	v_exp_f32_e32 v112, v112
	v_exp_f32_e32 v113, v113
	v_pk_mul_f32 v[100:101], v[100:101], v[114:115] op_sel_hi:[1,0]
	v_add_f32_e32 v112, 1.0, v112
	v_add_f32_e32 v113, 1.0, v113
	v_rcp_f32_e32 v112, v112
	v_rcp_f32_e32 v113, v113
	s_nop 0
	v_pk_mul_f32 v[110:111], v[110:111], v[112:113]
	s_nop 0
	v_pk_mul_f32 v[108:109], v[108:109], v[110:111]
	s_nop 0
	v_cvt_pk_bf16_f32 v107, v108, v109
	v_mad_i64_i32 v[108:109], s[20:21], v126, s1, v[122:123]
	v_lshl_add_u64 v[108:109], v[108:109], 0, v[124:125]
	global_store_dwordx2 v[108:109], v[106:107], off
	v_mul_f32_e32 v106, 0xbfb8aa3b, v102
	v_mul_f32_e32 v107, 0xbfb8aa3b, v103
	v_exp_f32_e32 v106, v106
	v_exp_f32_e32 v107, v107
	v_add_f32_e32 v106, 1.0, v106
	v_add_f32_e32 v107, 1.0, v107
	v_rcp_f32_e32 v106, v106
	v_rcp_f32_e32 v107, v107
	s_nop 0
	v_pk_mul_f32 v[102:103], v[102:103], v[106:107]
	s_nop 0
	v_pk_mul_f32 v[98:99], v[98:99], v[102:103]
	v_pk_mul_f32 v[102:103], v[104:105], v[114:115] op_sel_hi:[1,0]
	v_or_b32_e32 v106, 32, v140
	v_mul_f32_e32 v104, 0xbfb8aa3b, v102
	v_mul_f32_e32 v105, 0xbfb8aa3b, v103
	v_exp_f32_e32 v104, v104
	v_exp_f32_e32 v105, v105
	v_cvt_pk_bf16_f32 v98, v98, v99
	v_ashrrev_i32_e32 v107, 31, v106
	v_add_f32_e32 v104, 1.0, v104
	v_add_f32_e32 v105, 1.0, v105
	v_rcp_f32_e32 v104, v104
	v_rcp_f32_e32 v105, v105
	s_nop 0
	v_pk_mul_f32 v[102:103], v[102:103], v[104:105]
	s_nop 0
	v_pk_mul_f32 v[100:101], v[100:101], v[102:103]
	s_nop 0
	v_cvt_pk_bf16_f32 v99, v100, v101
	global_store_dwordx2 v[108:109], v[98:99], off offset:128
	v_add_f32_e32 v212, v212, v213
	v_add_f32_e32 v214, v214, v215
	v_add_f32_e32 v212, v212, v214
	v_mov_b32_e32 v213, v212
	s_nop 1
	v_permlane16_swap_b32_e32 v212, v213
	v_add_f32_e32 v212, v212, v213
	v_mov_b32_e32 v213, v212
	s_nop 1
	v_permlane32_swap_b32_e32 v212, v213
	v_add_f32_e32 v98, v212, v213
	v_fmamk_f32 v98, v98, 0x3a800000, v161
	v_cmp_gt_f32_e32 vcc, s62, v98
	v_mul_f32_e32 v99, 0x4b800000, v98
	s_nop 0
	v_cndmask_b32_e32 v98, v98, v99, vcc
	v_rsq_f32_e32 v98, v98
	s_nop 0
	v_mul_f32_e32 v99, 0x45800000, v98
	v_cndmask_b32_e32 v98, v98, v99, vcc
	v_pk_mul_f32 v[94:95], v[94:95], v[98:99] op_sel_hi:[1,0]
	s_nop 0
	v_mul_f32_e32 v99, 0xbfb8aa3b, v94
	v_exp_f32_e32 v99, v99
	s_nop 0
	v_add_f32_e32 v99, 1.0, v99
	v_rcp_f32_e32 v100, v99
	v_mul_f32_e32 v99, 0xbfb8aa3b, v95
	v_exp_f32_e32 v99, v99
	s_nop 0
	v_add_f32_e32 v99, 1.0, v99
	v_rcp_f32_e32 v101, v99
	v_pk_mul_f32 v[90:91], v[90:91], v[98:99] op_sel_hi:[1,0]
	v_pk_mul_f32 v[92:93], v[92:93], v[98:99] op_sel_hi:[1,0]
	v_pk_mul_f32 v[86:87], v[86:87], v[98:99] op_sel_hi:[1,0]
	v_pk_mul_f32 v[94:95], v[94:95], v[100:101]
	v_pk_mul_f32 v[82:83], v[82:83], v[98:99] op_sel_hi:[1,0]
	v_pk_mul_f32 v[90:91], v[90:91], v[94:95]
	v_pk_mul_f32 v[94:95], v[96:97], v[98:99] op_sel_hi:[1,0]
	v_cvt_pk_bf16_f32 v90, v90, v91
	v_mul_f32_e32 v96, 0xbfb8aa3b, v94
	v_mul_f32_e32 v97, 0xbfb8aa3b, v95
	v_exp_f32_e32 v96, v96
	v_exp_f32_e32 v97, v97
	v_pk_mul_f32 v[84:85], v[84:85], v[98:99] op_sel_hi:[1,0]
	v_add_f32_e32 v96, 1.0, v96
	v_add_f32_e32 v97, 1.0, v97
	v_rcp_f32_e32 v96, v96
	v_rcp_f32_e32 v97, v97
	s_nop 0
	v_pk_mul_f32 v[94:95], v[94:95], v[96:97]
	s_nop 0
	v_pk_mul_f32 v[92:93], v[92:93], v[94:95]
	s_nop 0
	v_cvt_pk_bf16_f32 v91, v92, v93
	v_mad_i64_i32 v[92:93], s[20:21], v106, s1, v[122:123]
	v_lshl_add_u64 v[92:93], v[92:93], 0, v[124:125]
	global_store_dwordx2 v[92:93], v[90:91], off
	v_mul_f32_e32 v90, 0xbfb8aa3b, v86
	v_mul_f32_e32 v91, 0xbfb8aa3b, v87
	v_exp_f32_e32 v90, v90
	v_exp_f32_e32 v91, v91
	v_add_f32_e32 v90, 1.0, v90
	v_add_f32_e32 v91, 1.0, v91
	v_rcp_f32_e32 v90, v90
	v_rcp_f32_e32 v91, v91
	s_nop 0
	v_pk_mul_f32 v[86:87], v[86:87], v[90:91]
	s_nop 0
	v_pk_mul_f32 v[82:83], v[82:83], v[86:87]
	v_pk_mul_f32 v[86:87], v[88:89], v[98:99] op_sel_hi:[1,0]
	v_or_b32_e32 v90, 48, v140
	v_mul_f32_e32 v88, 0xbfb8aa3b, v86
	v_mul_f32_e32 v89, 0xbfb8aa3b, v87
	v_exp_f32_e32 v88, v88
	v_exp_f32_e32 v89, v89
	v_cvt_pk_bf16_f32 v82, v82, v83
	v_ashrrev_i32_e32 v91, 31, v90
	v_add_f32_e32 v88, 1.0, v88
	v_add_f32_e32 v89, 1.0, v89
	v_rcp_f32_e32 v88, v88
	v_rcp_f32_e32 v89, v89
	s_nop 0
	v_pk_mul_f32 v[86:87], v[86:87], v[88:89]
	s_nop 0
	v_pk_mul_f32 v[84:85], v[84:85], v[86:87]
	s_nop 0
	v_cvt_pk_bf16_f32 v83, v84, v85
	global_store_dwordx2 v[92:93], v[82:83], off offset:128
	v_add_f32_e32 v216, v216, v217
	v_add_f32_e32 v218, v218, v219
	v_add_f32_e32 v216, v216, v218
	v_mov_b32_e32 v217, v216
	s_nop 1
	v_permlane16_swap_b32_e32 v216, v217
	v_add_f32_e32 v216, v216, v217
	v_mov_b32_e32 v217, v216
	s_nop 1
	v_permlane32_swap_b32_e32 v216, v217
	v_add_f32_e32 v82, v216, v217
	v_fmamk_f32 v82, v82, 0x3a800000, v161
	v_cmp_gt_f32_e32 vcc, s62, v82
	v_mul_f32_e32 v83, 0x4b800000, v82
	s_nop 0
	v_cndmask_b32_e32 v82, v82, v83, vcc
	v_rsq_f32_e32 v82, v82
	s_nop 0
	v_mul_f32_e32 v83, 0x45800000, v82
	v_cndmask_b32_e32 v82, v82, v83, vcc
	v_pk_mul_f32 v[78:79], v[78:79], v[82:83] op_sel_hi:[1,0]
	s_nop 0
	v_mul_f32_e32 v83, 0xbfb8aa3b, v78
	v_exp_f32_e32 v83, v83
	s_nop 0
	v_add_f32_e32 v83, 1.0, v83
	v_rcp_f32_e32 v84, v83
	v_mul_f32_e32 v83, 0xbfb8aa3b, v79
	v_exp_f32_e32 v83, v83
	s_nop 0
	v_add_f32_e32 v83, 1.0, v83
	v_rcp_f32_e32 v85, v83
	v_pk_mul_f32 v[74:75], v[74:75], v[82:83] op_sel_hi:[1,0]
	v_pk_mul_f32 v[76:77], v[76:77], v[82:83] op_sel_hi:[1,0]
	v_pk_mul_f32 v[70:71], v[70:71], v[82:83] op_sel_hi:[1,0]
	v_pk_mul_f32 v[78:79], v[78:79], v[84:85]
	v_pk_mul_f32 v[66:67], v[66:67], v[82:83] op_sel_hi:[1,0]
	v_pk_mul_f32 v[74:75], v[74:75], v[78:79]
	v_pk_mul_f32 v[78:79], v[80:81], v[82:83] op_sel_hi:[1,0]
	v_cvt_pk_bf16_f32 v74, v74, v75
	v_mul_f32_e32 v80, 0xbfb8aa3b, v78
	v_mul_f32_e32 v81, 0xbfb8aa3b, v79
	v_exp_f32_e32 v80, v80
	v_exp_f32_e32 v81, v81
	v_pk_mul_f32 v[68:69], v[68:69], v[82:83] op_sel_hi:[1,0]
	v_add_f32_e32 v80, 1.0, v80
	v_add_f32_e32 v81, 1.0, v81
	v_rcp_f32_e32 v80, v80
	v_rcp_f32_e32 v81, v81
	s_nop 0
	v_pk_mul_f32 v[78:79], v[78:79], v[80:81]
	s_nop 0
	v_pk_mul_f32 v[76:77], v[76:77], v[78:79]
	s_nop 0
	v_cvt_pk_bf16_f32 v75, v76, v77
	v_mad_i64_i32 v[76:77], s[20:21], v90, s1, v[122:123]
	v_lshl_add_u64 v[76:77], v[76:77], 0, v[124:125]
	global_store_dwordx2 v[76:77], v[74:75], off
	v_mul_f32_e32 v74, 0xbfb8aa3b, v70
	v_mul_f32_e32 v75, 0xbfb8aa3b, v71
	v_exp_f32_e32 v74, v74
	v_exp_f32_e32 v75, v75
	v_add_f32_e32 v74, 1.0, v74
	v_add_f32_e32 v75, 1.0, v75
	v_rcp_f32_e32 v74, v74
	v_rcp_f32_e32 v75, v75
	s_nop 0
	v_pk_mul_f32 v[70:71], v[70:71], v[74:75]
	s_nop 0
	v_pk_mul_f32 v[66:67], v[66:67], v[70:71]
	v_pk_mul_f32 v[70:71], v[72:73], v[82:83] op_sel_hi:[1,0]
	v_add_u32_e32 v74, 0x80, v140
	v_mul_f32_e32 v72, 0xbfb8aa3b, v70
	v_mul_f32_e32 v73, 0xbfb8aa3b, v71
	v_exp_f32_e32 v72, v72
	v_exp_f32_e32 v73, v73
	v_cvt_pk_bf16_f32 v66, v66, v67
	v_ashrrev_i32_e32 v75, 31, v74
	v_add_f32_e32 v72, 1.0, v72
	v_add_f32_e32 v73, 1.0, v73
	v_rcp_f32_e32 v72, v72
	v_rcp_f32_e32 v73, v73
	s_nop 0
	v_pk_mul_f32 v[70:71], v[70:71], v[72:73]
	s_nop 0
	v_pk_mul_f32 v[68:69], v[68:69], v[70:71]
	s_nop 0
	v_cvt_pk_bf16_f32 v67, v68, v69
	global_store_dwordx2 v[76:77], v[66:67], off offset:128
	v_add_f32_e32 v220, v220, v221
	v_add_f32_e32 v222, v222, v223
	v_add_f32_e32 v220, v220, v222
	v_mov_b32_e32 v221, v220
	s_nop 1
	v_permlane16_swap_b32_e32 v220, v221
	v_add_f32_e32 v220, v220, v221
	v_mov_b32_e32 v221, v220
	s_nop 1
	v_permlane32_swap_b32_e32 v220, v221
	v_add_f32_e32 v66, v220, v221
	v_fmamk_f32 v66, v66, 0x3a800000, v161
	v_cmp_gt_f32_e32 vcc, s62, v66
	v_mul_f32_e32 v67, 0x4b800000, v66
	s_nop 0
	v_cndmask_b32_e32 v66, v66, v67, vcc
	v_rsq_f32_e32 v66, v66
	s_nop 0
	v_mul_f32_e32 v67, 0x45800000, v66
	v_cndmask_b32_e32 v66, v66, v67, vcc
	v_pk_mul_f32 v[62:63], v[62:63], v[66:67] op_sel_hi:[1,0]
	s_nop 0
	v_mul_f32_e32 v67, 0xbfb8aa3b, v62
	v_exp_f32_e32 v67, v67
	s_nop 0
	v_add_f32_e32 v67, 1.0, v67
	v_rcp_f32_e32 v68, v67
	v_mul_f32_e32 v67, 0xbfb8aa3b, v63
	v_exp_f32_e32 v67, v67
	s_nop 0
	v_add_f32_e32 v67, 1.0, v67
	v_rcp_f32_e32 v69, v67
	v_pk_mul_f32 v[58:59], v[58:59], v[66:67] op_sel_hi:[1,0]
	v_pk_mul_f32 v[60:61], v[60:61], v[66:67] op_sel_hi:[1,0]
	v_pk_mul_f32 v[54:55], v[54:55], v[66:67] op_sel_hi:[1,0]
	v_pk_mul_f32 v[62:63], v[62:63], v[68:69]
	v_pk_mul_f32 v[50:51], v[50:51], v[66:67] op_sel_hi:[1,0]
	v_pk_mul_f32 v[58:59], v[58:59], v[62:63]
	v_pk_mul_f32 v[62:63], v[64:65], v[66:67] op_sel_hi:[1,0]
	v_cvt_pk_bf16_f32 v58, v58, v59
	v_mul_f32_e32 v64, 0xbfb8aa3b, v62
	v_mul_f32_e32 v65, 0xbfb8aa3b, v63
	v_exp_f32_e32 v64, v64
	v_exp_f32_e32 v65, v65
	v_pk_mul_f32 v[52:53], v[52:53], v[66:67] op_sel_hi:[1,0]
	v_add_f32_e32 v64, 1.0, v64
	v_add_f32_e32 v65, 1.0, v65
	v_rcp_f32_e32 v64, v64
	v_rcp_f32_e32 v65, v65
	s_nop 0
	v_pk_mul_f32 v[62:63], v[62:63], v[64:65]
	s_nop 0
	v_pk_mul_f32 v[60:61], v[60:61], v[62:63]
	s_nop 0
	v_cvt_pk_bf16_f32 v59, v60, v61
	v_mad_i64_i32 v[60:61], s[20:21], v74, s1, v[122:123]
	v_lshl_add_u64 v[60:61], v[60:61], 0, v[124:125]
	global_store_dwordx2 v[60:61], v[58:59], off
	v_mul_f32_e32 v58, 0xbfb8aa3b, v54
	v_mul_f32_e32 v59, 0xbfb8aa3b, v55
	v_exp_f32_e32 v58, v58
	v_exp_f32_e32 v59, v59
	v_add_f32_e32 v58, 1.0, v58
	v_add_f32_e32 v59, 1.0, v59
	v_rcp_f32_e32 v58, v58
	v_rcp_f32_e32 v59, v59
	s_nop 0
	v_pk_mul_f32 v[54:55], v[54:55], v[58:59]
	s_nop 0
	v_pk_mul_f32 v[50:51], v[50:51], v[54:55]
	v_pk_mul_f32 v[54:55], v[56:57], v[66:67] op_sel_hi:[1,0]
	v_add_u32_e32 v58, 0x90, v140
	v_mul_f32_e32 v56, 0xbfb8aa3b, v54
	v_mul_f32_e32 v57, 0xbfb8aa3b, v55
	v_exp_f32_e32 v56, v56
	v_exp_f32_e32 v57, v57
	v_cvt_pk_bf16_f32 v50, v50, v51
	v_ashrrev_i32_e32 v59, 31, v58
	v_add_f32_e32 v56, 1.0, v56
	v_add_f32_e32 v57, 1.0, v57
	v_rcp_f32_e32 v56, v56
	v_rcp_f32_e32 v57, v57
	s_nop 0
	v_pk_mul_f32 v[54:55], v[54:55], v[56:57]
	s_nop 0
	v_pk_mul_f32 v[52:53], v[52:53], v[54:55]
	s_nop 0
	v_cvt_pk_bf16_f32 v51, v52, v53
	global_store_dwordx2 v[60:61], v[50:51], off offset:128
	v_add_f32_e32 v224, v224, v225
	v_add_f32_e32 v226, v226, v227
	v_add_f32_e32 v224, v224, v226
	v_mov_b32_e32 v225, v224
	s_nop 1
	v_permlane16_swap_b32_e32 v224, v225
	v_add_f32_e32 v224, v224, v225
	v_mov_b32_e32 v225, v224
	s_nop 1
	v_permlane32_swap_b32_e32 v224, v225
	v_add_f32_e32 v50, v224, v225
	v_fmamk_f32 v50, v50, 0x3a800000, v161
	v_cmp_gt_f32_e32 vcc, s62, v50
	v_mul_f32_e32 v51, 0x4b800000, v50
	s_nop 0
	v_cndmask_b32_e32 v50, v50, v51, vcc
	v_rsq_f32_e32 v50, v50
	s_nop 0
	v_mul_f32_e32 v51, 0x45800000, v50
	v_cndmask_b32_e32 v50, v50, v51, vcc
	v_pk_mul_f32 v[46:47], v[46:47], v[50:51] op_sel_hi:[1,0]
	s_nop 0
	v_mul_f32_e32 v51, 0xbfb8aa3b, v46
	v_exp_f32_e32 v51, v51
	s_nop 0
	v_add_f32_e32 v51, 1.0, v51
	v_rcp_f32_e32 v52, v51
	v_mul_f32_e32 v51, 0xbfb8aa3b, v47
	v_exp_f32_e32 v51, v51
	s_nop 0
	v_add_f32_e32 v51, 1.0, v51
	v_rcp_f32_e32 v53, v51
	v_pk_mul_f32 v[42:43], v[42:43], v[50:51] op_sel_hi:[1,0]
	v_pk_mul_f32 v[44:45], v[44:45], v[50:51] op_sel_hi:[1,0]
	v_pk_mul_f32 v[38:39], v[38:39], v[50:51] op_sel_hi:[1,0]
	v_pk_mul_f32 v[46:47], v[46:47], v[52:53]
	v_pk_mul_f32 v[34:35], v[34:35], v[50:51] op_sel_hi:[1,0]
	v_pk_mul_f32 v[42:43], v[42:43], v[46:47]
	v_pk_mul_f32 v[46:47], v[48:49], v[50:51] op_sel_hi:[1,0]
	v_cvt_pk_bf16_f32 v42, v42, v43
	v_mul_f32_e32 v48, 0xbfb8aa3b, v46
	v_mul_f32_e32 v49, 0xbfb8aa3b, v47
	v_exp_f32_e32 v48, v48
	v_exp_f32_e32 v49, v49
	v_pk_mul_f32 v[36:37], v[36:37], v[50:51] op_sel_hi:[1,0]
	v_add_f32_e32 v48, 1.0, v48
	v_add_f32_e32 v49, 1.0, v49
	v_rcp_f32_e32 v48, v48
	v_rcp_f32_e32 v49, v49
	s_nop 0
	v_pk_mul_f32 v[46:47], v[46:47], v[48:49]
	s_nop 0
	v_pk_mul_f32 v[44:45], v[44:45], v[46:47]
	s_nop 0
	v_cvt_pk_bf16_f32 v43, v44, v45
	v_mad_i64_i32 v[44:45], s[20:21], v58, s1, v[122:123]
	v_lshl_add_u64 v[44:45], v[44:45], 0, v[124:125]
	global_store_dwordx2 v[44:45], v[42:43], off
	v_mul_f32_e32 v42, 0xbfb8aa3b, v38
	v_mul_f32_e32 v43, 0xbfb8aa3b, v39
	v_exp_f32_e32 v42, v42
	v_exp_f32_e32 v43, v43
	v_add_f32_e32 v42, 1.0, v42
	v_add_f32_e32 v43, 1.0, v43
	v_rcp_f32_e32 v42, v42
	v_rcp_f32_e32 v43, v43
	s_nop 0
	v_pk_mul_f32 v[38:39], v[38:39], v[42:43]
	s_nop 0
	v_pk_mul_f32 v[34:35], v[34:35], v[38:39]
	v_pk_mul_f32 v[38:39], v[40:41], v[50:51] op_sel_hi:[1,0]
	v_add_u32_e32 v42, 0xa0, v140
	v_mul_f32_e32 v40, 0xbfb8aa3b, v38
	v_mul_f32_e32 v41, 0xbfb8aa3b, v39
	v_exp_f32_e32 v40, v40
	v_exp_f32_e32 v41, v41
	v_cvt_pk_bf16_f32 v34, v34, v35
	v_ashrrev_i32_e32 v43, 31, v42
	v_add_f32_e32 v40, 1.0, v40
	v_add_f32_e32 v41, 1.0, v41
	v_rcp_f32_e32 v40, v40
	v_rcp_f32_e32 v41, v41
	s_nop 0
	v_pk_mul_f32 v[38:39], v[38:39], v[40:41]
	s_nop 0
	v_pk_mul_f32 v[36:37], v[36:37], v[38:39]
	s_nop 0
	v_cvt_pk_bf16_f32 v35, v36, v37
	global_store_dwordx2 v[44:45], v[34:35], off offset:128
	v_add_f32_e32 v228, v228, v229
	v_add_f32_e32 v230, v230, v231
	v_add_f32_e32 v228, v228, v230
	v_mov_b32_e32 v229, v228
	s_nop 1
	v_permlane16_swap_b32_e32 v228, v229
	v_add_f32_e32 v228, v228, v229
	v_mov_b32_e32 v229, v228
	s_nop 1
	v_permlane32_swap_b32_e32 v228, v229
	v_add_f32_e32 v34, v228, v229
	v_fmamk_f32 v34, v34, 0x3a800000, v161
	v_cmp_gt_f32_e32 vcc, s62, v34
	v_mul_f32_e32 v35, 0x4b800000, v34
	s_nop 0
	v_cndmask_b32_e32 v34, v34, v35, vcc
	v_rsq_f32_e32 v34, v34
	s_nop 0
	v_mul_f32_e32 v35, 0x45800000, v34
	v_cndmask_b32_e32 v34, v34, v35, vcc
	v_pk_mul_f32 v[30:31], v[30:31], v[34:35] op_sel_hi:[1,0]
	s_nop 0
	v_mul_f32_e32 v35, 0xbfb8aa3b, v30
	v_exp_f32_e32 v35, v35
	s_nop 0
	v_add_f32_e32 v35, 1.0, v35
	v_rcp_f32_e32 v36, v35
	v_mul_f32_e32 v35, 0xbfb8aa3b, v31
	v_exp_f32_e32 v35, v35
	s_nop 0
	v_add_f32_e32 v35, 1.0, v35
	v_rcp_f32_e32 v37, v35
	v_pk_mul_f32 v[26:27], v[26:27], v[34:35] op_sel_hi:[1,0]
	v_pk_mul_f32 v[28:29], v[28:29], v[34:35] op_sel_hi:[1,0]
	v_pk_mul_f32 v[22:23], v[22:23], v[34:35] op_sel_hi:[1,0]
	v_pk_mul_f32 v[30:31], v[30:31], v[36:37]
	v_pk_mul_f32 v[18:19], v[18:19], v[34:35] op_sel_hi:[1,0]
	v_pk_mul_f32 v[26:27], v[26:27], v[30:31]
	v_pk_mul_f32 v[30:31], v[32:33], v[34:35] op_sel_hi:[1,0]
	v_cvt_pk_bf16_f32 v26, v26, v27
	v_mul_f32_e32 v32, 0xbfb8aa3b, v30
	v_mul_f32_e32 v33, 0xbfb8aa3b, v31
	v_exp_f32_e32 v32, v32
	v_exp_f32_e32 v33, v33
	v_pk_mul_f32 v[20:21], v[20:21], v[34:35] op_sel_hi:[1,0]
	v_add_f32_e32 v32, 1.0, v32
	v_add_f32_e32 v33, 1.0, v33
	v_rcp_f32_e32 v32, v32
	v_rcp_f32_e32 v33, v33
	s_nop 0
	v_pk_mul_f32 v[30:31], v[30:31], v[32:33]
	s_nop 0
	v_pk_mul_f32 v[28:29], v[28:29], v[30:31]
	s_nop 0
	v_cvt_pk_bf16_f32 v27, v28, v29
	v_mad_i64_i32 v[28:29], s[20:21], v42, s1, v[122:123]
	v_lshl_add_u64 v[28:29], v[28:29], 0, v[124:125]
	global_store_dwordx2 v[28:29], v[26:27], off
	v_mul_f32_e32 v26, 0xbfb8aa3b, v22
	v_mul_f32_e32 v27, 0xbfb8aa3b, v23
	v_exp_f32_e32 v26, v26
	v_exp_f32_e32 v27, v27
	v_add_f32_e32 v26, 1.0, v26
	v_add_f32_e32 v27, 1.0, v27
	v_rcp_f32_e32 v26, v26
	v_rcp_f32_e32 v27, v27
	s_nop 0
	v_pk_mul_f32 v[22:23], v[22:23], v[26:27]
	s_nop 0
	v_pk_mul_f32 v[18:19], v[18:19], v[22:23]
	v_pk_mul_f32 v[22:23], v[24:25], v[34:35] op_sel_hi:[1,0]
	v_add_u32_e32 v26, 0xb0, v140
	v_mul_f32_e32 v24, 0xbfb8aa3b, v22
	v_mul_f32_e32 v25, 0xbfb8aa3b, v23
	v_exp_f32_e32 v24, v24
	v_exp_f32_e32 v25, v25
	v_cvt_pk_bf16_f32 v18, v18, v19
	v_ashrrev_i32_e32 v27, 31, v26
	v_add_f32_e32 v24, 1.0, v24
	v_add_f32_e32 v25, 1.0, v25
	v_rcp_f32_e32 v24, v24
	v_rcp_f32_e32 v25, v25
	s_nop 0
	v_pk_mul_f32 v[22:23], v[22:23], v[24:25]
	s_nop 0
	v_pk_mul_f32 v[20:21], v[20:21], v[22:23]
	s_nop 0
	v_cvt_pk_bf16_f32 v19, v20, v21
	global_store_dwordx2 v[28:29], v[18:19], off offset:128
	v_add_f32_e32 v232, v232, v233
	v_add_f32_e32 v234, v234, v235
	v_add_f32_e32 v232, v232, v234
	v_mov_b32_e32 v233, v232
	s_nop 1
	v_permlane16_swap_b32_e32 v232, v233
	v_add_f32_e32 v232, v232, v233
	v_mov_b32_e32 v233, v232
	s_nop 1
	v_permlane32_swap_b32_e32 v232, v233
	v_add_f32_e32 v18, v232, v233
	v_fmamk_f32 v18, v18, 0x3a800000, v161
	v_cmp_gt_f32_e32 vcc, s62, v18
	v_mul_f32_e32 v19, 0x4b800000, v18
	s_nop 0
	v_cndmask_b32_e32 v18, v18, v19, vcc
	v_rsq_f32_e32 v18, v18
	s_nop 0
	v_mul_f32_e32 v19, 0x45800000, v18
	v_cndmask_b32_e32 v18, v18, v19, vcc
	v_pk_mul_f32 v[14:15], v[14:15], v[18:19] op_sel_hi:[1,0]
	s_andn2_b64 vcc, exec, s[6:7]
	v_mul_f32_e32 v19, 0xbfb8aa3b, v14
	v_exp_f32_e32 v19, v19
	s_nop 0
	v_add_f32_e32 v19, 1.0, v19
	v_rcp_f32_e32 v20, v19
	v_mul_f32_e32 v19, 0xbfb8aa3b, v15
	v_exp_f32_e32 v19, v19
	s_nop 0
	v_add_f32_e32 v19, 1.0, v19
	v_rcp_f32_e32 v21, v19
	v_pk_mul_f32 v[10:11], v[10:11], v[18:19] op_sel_hi:[1,0]
	v_pk_mul_f32 v[12:13], v[12:13], v[18:19] op_sel_hi:[1,0]
	v_pk_mul_f32 v[6:7], v[6:7], v[18:19] op_sel_hi:[1,0]
	v_pk_mul_f32 v[14:15], v[14:15], v[20:21]
	v_pk_mul_f32 v[2:3], v[2:3], v[18:19] op_sel_hi:[1,0]
	v_pk_mul_f32 v[10:11], v[10:11], v[14:15]
	v_pk_mul_f32 v[14:15], v[16:17], v[18:19] op_sel_hi:[1,0]
	v_cvt_pk_bf16_f32 v10, v10, v11
	v_mul_f32_e32 v16, 0xbfb8aa3b, v14
	v_mul_f32_e32 v17, 0xbfb8aa3b, v15
	v_exp_f32_e32 v16, v16
	v_exp_f32_e32 v17, v17
	v_pk_mul_f32 v[4:5], v[4:5], v[18:19] op_sel_hi:[1,0]
	v_add_f32_e32 v16, 1.0, v16
	v_add_f32_e32 v17, 1.0, v17
	v_rcp_f32_e32 v16, v16
	v_rcp_f32_e32 v17, v17
	s_nop 0
	v_pk_mul_f32 v[14:15], v[14:15], v[16:17]
	s_nop 0
	v_pk_mul_f32 v[12:13], v[12:13], v[14:15]
	s_nop 0
	v_cvt_pk_bf16_f32 v11, v12, v13
	v_mad_i64_i32 v[12:13], s[20:21], v26, s1, v[122:123]
	v_lshl_add_u64 v[12:13], v[12:13], 0, v[124:125]
	global_store_dwordx2 v[12:13], v[10:11], off
	v_mul_f32_e32 v10, 0xbfb8aa3b, v6
	v_mul_f32_e32 v11, 0xbfb8aa3b, v7
	v_exp_f32_e32 v10, v10
	v_exp_f32_e32 v11, v11
	s_mov_b64 s[20:21], -1
	v_add_f32_e32 v10, 1.0, v10
	v_add_f32_e32 v11, 1.0, v11
	v_rcp_f32_e32 v10, v10
	v_rcp_f32_e32 v11, v11
	s_nop 0
	v_pk_mul_f32 v[6:7], v[6:7], v[10:11]
	s_nop 0
	v_pk_mul_f32 v[2:3], v[2:3], v[6:7]
	v_pk_mul_f32 v[6:7], v[8:9], v[18:19] op_sel_hi:[1,0]
	v_cvt_pk_bf16_f32 v2, v2, v3
	v_mul_f32_e32 v8, 0xbfb8aa3b, v6
	v_mul_f32_e32 v9, 0xbfb8aa3b, v7
	v_exp_f32_e32 v8, v8
	v_exp_f32_e32 v9, v9
	v_add_f32_e32 v8, 1.0, v8
	v_add_f32_e32 v9, 1.0, v9
	v_rcp_f32_e32 v8, v8
	v_rcp_f32_e32 v9, v9
	s_nop 0
	v_pk_mul_f32 v[6:7], v[6:7], v[8:9]
	s_nop 0
	v_pk_mul_f32 v[4:5], v[4:5], v[6:7]
	s_nop 0
	v_cvt_pk_bf16_f32 v3, v4, v5
	global_store_dwordx2 v[12:13], v[2:3], off offset:128
	s_cbranch_vccnz .LBB0_1598
	s_andn2_b64 vcc, exec, s[4:5]
	s_cbranch_vccnz .LBB0_1597
	s_barrier
	s_branch .LBB0_1597
